# ragged-round overlap + hand-written LDS-free P1 tail (small-weight transposes, all loads up front)
# speedup vs baseline: 1.0036x; 1.0036x over previous
; #define LAS __attribute__((address_space(3)))
; __device__ __forceinline__ void transpose_item_fp8(const float* W, int N, unsigned char* W8, int pitch, int kofs, int k0, int n_src, int n_dst, float scale, LAS float* scr, int lane) {
;     ...
;     for (int i = 0; i < 8; ++i) v[i] = *(const f32x4*)(W + (size_t)(k0 + r8 + 8 * i) * N + n_src + 4 * c4);
; #pragma unroll
;     for (int i = 0; i < 8; ++i) { LAS float* d = scr + (r8 + 8 * i) * 33 + 4 * c4; d[0] = v[i][0]; d[1] = v[i][1]; d[2] = v[i][2]; d[3] = v[i][3]; }
;     asm volatile("s_waitcnt lgkmcnt(0)" ::: "memory");
;     const int n = lane & 31, cp = lane >> 5;
; #pragma unroll
;     for (int q = 0; q < 2; ++q) { const int ck = (2 * cp + q) * 16; const LAS float* sp = scr + ck * 33 + n; u32x4 o;
; #pragma unroll
;         for (int w = 0; w < 4; ++w) o[w] = pack_fp8x4(sp[(4 * w) * 33] * scale, sp[(4 * w + 1) * 33] * scale, sp[(4 * w + 2) * 33] * scale, sp[(4 * w + 3) * 33] * scale);
;         *(u32x4*)(W8 + (size_t)(n_dst + n) * pitch + kofs + k0 + ck) = o; }
; __global__ void __launch_bounds__(512, 2) hybrid_fwd(Args a) {
;     ...
;             const int nwg = (M / 256) * (a.n_fp8 > 0 ? a.n_fp8 : a.n_bf16), rem = nwg % G; const int first = rem ? rem : 0, nhelp = G - first;
;             if (bx >= first) {
;                 LAS float* scr = (LAS float*)(lds + wave * 16384);
;                 const int gw = (bx - first) * 8 + wave, NGW = nhelp * 8;
;                 constexpr int I_PA = (1024 / 64) * (D / 32), I_PB = (512 / 64) * (D / 32), I_OUT = (D / 64) * (D / 32);
;                 for (int it = gw; it < I_PA + I_PB + I_OUT; it += NGW) {
;                     int r = it;
;                     if (r < I_PA) { const int nb = r % (D / 32), kb = r / (D / 32); transpose_item_fp8(a.w_pa, D, Wp8, 1536, 0, 64 * kb, 32 * nb, 32 * nb, W8_SCALE, scr, lane); continue; } r -= I_PA;
;                     if (r < I_PB) { const int nb = r % (D / 32), kb = r / (D / 32); transpose_item_fp8(a.w_pb, D, Wp8, 1536, 1024, 64 * kb, 32 * nb, 32 * nb, W8_SCALE, scr, lane); continue; } r -= I_PB;
;                     { const int nb = r % (D / 32), kb = r / (D / 32); transpose_item_fp8(a.w_out, D, Wout8, 2048, 0, 64 * kb, 32 * nb, 32 * nb, W8_SCALE, scr, lane); }
.LBB0_267:
	s_add_u32 s6, s90, 0x6e00000
	s_load_dword s0, s[70:71], 0x1c0
	s_addc_u32 s7, s91, 0
	s_add_u32 s98, s90, 0x7400000
	s_addc_u32 s99, s91, 0
	s_cmp_gt_i32 s46, 0
	s_waitcnt lgkmcnt(0)
	s_cselect_b32 s0, s46, s0
	s_abs_i32 s33, s92
	v_cvt_f32_u32_e32 v0, s33
	s_sub_i32 s4, 0, s33
	s_lshl_b32 s0, s0, 6
	s_ashr_i32 s1, s0, 31
	v_rcp_iflag_f32_e32 v0, v0
	s_abs_i32 s0, s0
	v_mul_f32_e32 v0, 0x4f7ffffe, v0
	v_cvt_u32_f32_e32 v0, v0
	s_nop 0
	v_readfirstlane_b32 s5, v0
	s_mul_i32 s4, s4, s5
	s_mul_hi_u32 s4, s5, s4
	s_add_i32 s4, s5, s4
	v_writelane_b32 v242, s4, 3
	s_mul_hi_u32 s4, s0, s4
	s_mul_i32 s4, s4, s33
	s_sub_i32 s0, s0, s4
	s_sub_i32 s4, s0, s33
	s_cmp_ge_u32 s0, s33
	s_cselect_b32 s0, s4, s0
	s_sub_i32 s4, s0, s33
	s_cmp_ge_u32 s0, s33
	s_cselect_b32 s0, s4, s0
	s_xor_b32 s0, s0, s1
	s_sub_i32 s0, s0, s1
	s_cmp_lt_i32 s2, s0
	s_cbranch_scc1 .LBB0_279
	s_cmp_lg_u32 s101, 1
	s_cbranch_scc1 .Ltail_orig
	s_load_dwordx4 s[12:15], s[70:71], 0x28
	s_load_dwordx2 s[10:11], s[70:71], 0x38
	v_mbcnt_lo_u32_b32 v113, -1, 0
	v_mbcnt_hi_u32_b32 v113, -1, v113
	v_and_b32_e32 v114, 7, v113
	v_lshrrev_b32_e32 v115, 3, v113
	v_lshlrev_b32_e32 v96, 16, v115
	v_lshl_or_b32 v96, v114, 4, v96
	v_add_u32_e32 v97, 0x2000, v96
	v_add_u32_e32 v98, 0x4000, v96
	v_add_u32_e32 v99, 0x6000, v96
	v_add_u32_e32 v100, 0x8000, v96
	v_add_u32_e32 v101, 0xa000, v96
	v_add_u32_e32 v102, 0xc000, v96
	v_add_u32_e32 v103, 0xe000, v96
	v_lshlrev_b32_e32 v104, 2, v114
	v_add_u32_e32 v105, 1, v104
	v_add_u32_e32 v106, 2, v104
	v_add_u32_e32 v107, 3, v104
	v_lshlrev_b32_e32 v108, 3, v115
	v_readfirstlane_b32 s9, v160
	s_lshr_b32 s9, s9, 6
	s_sub_u32 s8, s2, 64
	s_lshl_b32 s8, s8, 3
	s_add_u32 s8, s8, s9
	s_waitcnt lgkmcnt(0)
	s_add_u32 s9, s8, 0x0
	s_sub_u32 s4, s9, 0x400
	s_sub_u32 s5, s9, 0x600
	s_mov_b32 vcc_lo, 0x6e00400
	s_mov_b32 vcc_hi, 0x7400000
	s_cmp_lt_u32 s9, 0x600
	s_cselect_b32 s5, s4, s5
	s_cselect_b32 s0, s14, s10
	s_cselect_b32 s1, s15, s11
	s_cselect_b32 s100, vcc_lo, vcc_hi
	s_movk_i32 s4, 0x600
	s_movk_i32 vcc_lo, 0x800
	s_cselect_b32 s4, s4, vcc_lo
	s_mov_b32 vcc_hi, 0x6e00000
	s_cmp_lt_u32 s9, 0x400
	s_cselect_b32 s5, s9, s5
	s_cselect_b32 s0, s12, s0
	s_cselect_b32 s1, s13, s1
	s_cselect_b32 s100, vcc_hi, s100
	s_lshr_b32 s9, s5, 6
	s_and_b32 s5, s5, 63
	s_lshl_b32 vcc_lo, s9, 19
	s_lshl_b32 vcc_hi, s5, 7
	s_add_u32 vcc_lo, vcc_lo, vcc_hi
	s_add_u32 s0, s0, vcc_lo
	s_addc_u32 s1, s1, 0
	s_lshl_b32 s5, s5, 5
	s_mul_i32 s5, s5, s4
	s_lshl_b32 s9, s9, 6
	s_add_u32 s100, s100, s5
	s_add_u32 s100, s100, s9
	v_mov_b32_e32 v113, s4
	v_mad_u32_u24 v116, v104, v113, v108
	v_mad_u32_u24 v117, v105, v113, v108
	v_mad_u32_u24 v118, v106, v113, v108
	v_mad_u32_u24 v119, v107, v113, v108
	v_add_u32_e32 v116, s100, v116
	v_add_u32_e32 v117, s100, v117
	v_add_u32_e32 v118, s100, v118
	v_add_u32_e32 v119, s100, v119
	global_load_dwordx4 v[0:3], v96, s[0:1] nt
	global_load_dwordx4 v[4:7], v97, s[0:1] nt
	global_load_dwordx4 v[8:11], v98, s[0:1] nt
	global_load_dwordx4 v[12:15], v99, s[0:1] nt
	global_load_dwordx4 v[16:19], v100, s[0:1] nt
	global_load_dwordx4 v[20:23], v101, s[0:1] nt
	global_load_dwordx4 v[24:27], v102, s[0:1] nt
	global_load_dwordx4 v[28:31], v103, s[0:1] nt
	s_add_u32 s9, s8, 0x600
	s_sub_u32 s4, s9, 0x400
	s_sub_u32 s5, s9, 0x600
	s_mov_b32 vcc_lo, 0x6e00400
	s_mov_b32 vcc_hi, 0x7400000
	s_cmp_lt_u32 s9, 0x600
	s_cselect_b32 s5, s4, s5
	s_cselect_b32 s0, s14, s10
	s_cselect_b32 s1, s15, s11
	s_cselect_b32 s100, vcc_lo, vcc_hi
	s_movk_i32 s4, 0x600
	s_movk_i32 vcc_lo, 0x800
	s_cselect_b32 s4, s4, vcc_lo
	s_mov_b32 vcc_hi, 0x6e00000
	s_cmp_lt_u32 s9, 0x400
	s_cselect_b32 s5, s9, s5
	s_cselect_b32 s0, s12, s0
	s_cselect_b32 s1, s13, s1
	s_cselect_b32 s100, vcc_hi, s100
	s_lshr_b32 s9, s5, 6
	s_and_b32 s5, s5, 63
	s_lshl_b32 vcc_lo, s9, 19
	s_lshl_b32 vcc_hi, s5, 7
	s_add_u32 vcc_lo, vcc_lo, vcc_hi
	s_add_u32 s0, s0, vcc_lo
	s_addc_u32 s1, s1, 0
	s_lshl_b32 s5, s5, 5
	s_mul_i32 s5, s5, s4
	s_lshl_b32 s9, s9, 6
	s_add_u32 s100, s100, s5
	s_add_u32 s100, s100, s9
	v_mov_b32_e32 v113, s4
	v_mad_u32_u24 v120, v104, v113, v108
	v_mad_u32_u24 v121, v105, v113, v108
	v_mad_u32_u24 v122, v106, v113, v108
	v_mad_u32_u24 v123, v107, v113, v108
	v_add_u32_e32 v120, s100, v120
	v_add_u32_e32 v121, s100, v121
	v_add_u32_e32 v122, s100, v122
	v_add_u32_e32 v123, s100, v123
	global_load_dwordx4 v[32:35], v96, s[0:1] nt
	global_load_dwordx4 v[36:39], v97, s[0:1] nt
	global_load_dwordx4 v[40:43], v98, s[0:1] nt
	global_load_dwordx4 v[44:47], v99, s[0:1] nt
	global_load_dwordx4 v[48:51], v100, s[0:1] nt
	global_load_dwordx4 v[52:55], v101, s[0:1] nt
	global_load_dwordx4 v[56:59], v102, s[0:1] nt
	global_load_dwordx4 v[60:63], v103, s[0:1] nt
	s_cmp_ge_u32 s8, 0x200
	s_cbranch_scc1 .Ltail_two
; #define LAS __attribute__((address_space(3)))
; __device__ __forceinline__ void transpose_item_fp8(const float* W, int N, unsigned char* W8, int pitch, int kofs, int k0, int n_src, int n_dst, float scale, LAS float* scr, int lane) {
;     ...
;     for (int i = 0; i < 8; ++i) v[i] = *(const f32x4*)(W + (size_t)(k0 + r8 + 8 * i) * N + n_src + 4 * c4);
; #pragma unroll
;     for (int i = 0; i < 8; ++i) { LAS float* d = scr + (r8 + 8 * i) * 33 + 4 * c4; d[0] = v[i][0]; d[1] = v[i][1]; d[2] = v[i][2]; d[3] = v[i][3]; }
;     asm volatile("s_waitcnt lgkmcnt(0)" ::: "memory");
;     const int n = lane & 31, cp = lane >> 5;
; #pragma unroll
;     for (int q = 0; q < 2; ++q) { const int ck = (2 * cp + q) * 16; const LAS float* sp = scr + ck * 33 + n; u32x4 o;
; #pragma unroll
;         for (int w = 0; w < 4; ++w) o[w] = pack_fp8x4(sp[(4 * w) * 33] * scale, sp[(4 * w + 1) * 33] * scale, sp[(4 * w + 2) * 33] * scale, sp[(4 * w + 3) * 33] * scale);
;         *(u32x4*)(W8 + (size_t)(n_dst + n) * pitch + kofs + k0 + ck) = o; }
	s_add_u32 s9, s8, 0xc00
	s_sub_u32 s4, s9, 0x400
	s_sub_u32 s5, s9, 0x600
	s_mov_b32 vcc_lo, 0x6e00400
	s_mov_b32 vcc_hi, 0x7400000
	s_cmp_lt_u32 s9, 0x600
	s_cselect_b32 s5, s4, s5
	s_cselect_b32 s0, s14, s10
	s_cselect_b32 s1, s15, s11
	s_cselect_b32 s100, vcc_lo, vcc_hi
	s_movk_i32 s4, 0x600
	s_movk_i32 vcc_lo, 0x800
	s_cselect_b32 s4, s4, vcc_lo
	s_mov_b32 vcc_hi, 0x6e00000
	s_cmp_lt_u32 s9, 0x400
	s_cselect_b32 s5, s9, s5
	s_cselect_b32 s0, s12, s0
	s_cselect_b32 s1, s13, s1
	s_cselect_b32 s100, vcc_hi, s100
	s_lshr_b32 s9, s5, 6
	s_and_b32 s5, s5, 63
	s_lshl_b32 vcc_lo, s9, 19
	s_lshl_b32 vcc_hi, s5, 7
	s_add_u32 vcc_lo, vcc_lo, vcc_hi
	s_add_u32 s0, s0, vcc_lo
	s_addc_u32 s1, s1, 0
	s_lshl_b32 s5, s5, 5
	s_mul_i32 s5, s5, s4
	s_lshl_b32 s9, s9, 6
	s_add_u32 s100, s100, s5
	s_add_u32 s100, s100, s9
	v_mov_b32_e32 v113, s4
	v_mad_u32_u24 v124, v104, v113, v108
	v_mad_u32_u24 v125, v105, v113, v108
	v_mad_u32_u24 v126, v106, v113, v108
	v_mad_u32_u24 v127, v107, v113, v108
	v_add_u32_e32 v124, s100, v124
	v_add_u32_e32 v125, s100, v125
	v_add_u32_e32 v126, s100, v126
	v_add_u32_e32 v127, s100, v127
	global_load_dwordx4 v[64:67], v96, s[0:1] nt
	global_load_dwordx4 v[68:71], v97, s[0:1] nt
	global_load_dwordx4 v[72:75], v98, s[0:1] nt
	global_load_dwordx4 v[76:79], v99, s[0:1] nt
	global_load_dwordx4 v[80:83], v100, s[0:1] nt
	global_load_dwordx4 v[84:87], v101, s[0:1] nt
	global_load_dwordx4 v[88:91], v102, s[0:1] nt
	global_load_dwordx4 v[92:95], v103, s[0:1] nt
	s_mov_b32 s4, 0x42800000
	s_mov_b32 s5, 0x42800000
	s_waitcnt vmcnt(16)
	v_pk_mul_f32 v[0:1], v[0:1], s[4:5]
	v_pk_mul_f32 v[2:3], v[2:3], s[4:5]
	v_pk_mul_f32 v[4:5], v[4:5], s[4:5]
	v_pk_mul_f32 v[6:7], v[6:7], s[4:5]
	v_pk_mul_f32 v[8:9], v[8:9], s[4:5]
	v_pk_mul_f32 v[10:11], v[10:11], s[4:5]
	v_pk_mul_f32 v[12:13], v[12:13], s[4:5]
	v_pk_mul_f32 v[14:15], v[14:15], s[4:5]
	v_pk_mul_f32 v[16:17], v[16:17], s[4:5]
	v_pk_mul_f32 v[18:19], v[18:19], s[4:5]
	v_pk_mul_f32 v[20:21], v[20:21], s[4:5]
	v_pk_mul_f32 v[22:23], v[22:23], s[4:5]
	v_pk_mul_f32 v[24:25], v[24:25], s[4:5]
	v_pk_mul_f32 v[26:27], v[26:27], s[4:5]
	v_pk_mul_f32 v[28:29], v[28:29], s[4:5]
	v_pk_mul_f32 v[30:31], v[30:31], s[4:5]
	v_cvt_pk_fp8_f32 v109, v0, v4
	v_cvt_pk_fp8_f32 v110, v8, v12
	v_cvt_pk_fp8_f32 v111, v16, v20
	v_cvt_pk_fp8_f32 v112, v24, v28
	v_and_b32_e32 v109, 0xffff, v109
	v_and_b32_e32 v111, 0xffff, v111
	v_lshl_or_b32 v128, v110, 16, v109
	v_lshl_or_b32 v129, v112, 16, v111
	global_store_dwordx2 v116, v[128:129], s[90:91]
	v_cvt_pk_fp8_f32 v109, v1, v5
	v_cvt_pk_fp8_f32 v110, v9, v13
	v_cvt_pk_fp8_f32 v111, v17, v21
	v_cvt_pk_fp8_f32 v112, v25, v29
	v_and_b32_e32 v109, 0xffff, v109
	v_and_b32_e32 v111, 0xffff, v111
	v_lshl_or_b32 v130, v110, 16, v109
	v_lshl_or_b32 v131, v112, 16, v111
	global_store_dwordx2 v117, v[130:131], s[90:91]
	v_cvt_pk_fp8_f32 v109, v2, v6
	v_cvt_pk_fp8_f32 v110, v10, v14
	v_cvt_pk_fp8_f32 v111, v18, v22
	v_cvt_pk_fp8_f32 v112, v26, v30
	v_and_b32_e32 v109, 0xffff, v109
	v_and_b32_e32 v111, 0xffff, v111
	v_lshl_or_b32 v128, v110, 16, v109
	v_lshl_or_b32 v129, v112, 16, v111
	global_store_dwordx2 v118, v[128:129], s[90:91]
	v_cvt_pk_fp8_f32 v109, v3, v7
	v_cvt_pk_fp8_f32 v110, v11, v15
	v_cvt_pk_fp8_f32 v111, v19, v23
	v_cvt_pk_fp8_f32 v112, v27, v31
	v_and_b32_e32 v109, 0xffff, v109
	v_and_b32_e32 v111, 0xffff, v111
	v_lshl_or_b32 v130, v110, 16, v109
	v_lshl_or_b32 v131, v112, 16, v111
	global_store_dwordx2 v119, v[130:131], s[90:91]
	s_waitcnt vmcnt(12)
	v_pk_mul_f32 v[32:33], v[32:33], s[4:5]
	v_pk_mul_f32 v[34:35], v[34:35], s[4:5]
	v_pk_mul_f32 v[36:37], v[36:37], s[4:5]
	v_pk_mul_f32 v[38:39], v[38:39], s[4:5]
	v_pk_mul_f32 v[40:41], v[40:41], s[4:5]
	v_pk_mul_f32 v[42:43], v[42:43], s[4:5]
	v_pk_mul_f32 v[44:45], v[44:45], s[4:5]
	v_pk_mul_f32 v[46:47], v[46:47], s[4:5]
	v_pk_mul_f32 v[48:49], v[48:49], s[4:5]
	v_pk_mul_f32 v[50:51], v[50:51], s[4:5]
	v_pk_mul_f32 v[52:53], v[52:53], s[4:5]
	v_pk_mul_f32 v[54:55], v[54:55], s[4:5]
	v_pk_mul_f32 v[56:57], v[56:57], s[4:5]
	v_pk_mul_f32 v[58:59], v[58:59], s[4:5]
	v_pk_mul_f32 v[60:61], v[60:61], s[4:5]
	v_pk_mul_f32 v[62:63], v[62:63], s[4:5]
	v_cvt_pk_fp8_f32 v109, v32, v36
	v_cvt_pk_fp8_f32 v110, v40, v44
	v_cvt_pk_fp8_f32 v111, v48, v52
	v_cvt_pk_fp8_f32 v112, v56, v60
	v_and_b32_e32 v109, 0xffff, v109
	v_and_b32_e32 v111, 0xffff, v111
	v_lshl_or_b32 v128, v110, 16, v109
	v_lshl_or_b32 v129, v112, 16, v111
	global_store_dwordx2 v120, v[128:129], s[90:91]
	v_cvt_pk_fp8_f32 v109, v33, v37
	v_cvt_pk_fp8_f32 v110, v41, v45
	v_cvt_pk_fp8_f32 v111, v49, v53
	v_cvt_pk_fp8_f32 v112, v57, v61
	v_and_b32_e32 v109, 0xffff, v109
	v_and_b32_e32 v111, 0xffff, v111
	v_lshl_or_b32 v130, v110, 16, v109
	v_lshl_or_b32 v131, v112, 16, v111
	global_store_dwordx2 v121, v[130:131], s[90:91]
	v_cvt_pk_fp8_f32 v109, v34, v38
	v_cvt_pk_fp8_f32 v110, v42, v46
	v_cvt_pk_fp8_f32 v111, v50, v54
	v_cvt_pk_fp8_f32 v112, v58, v62
	v_and_b32_e32 v109, 0xffff, v109
	v_and_b32_e32 v111, 0xffff, v111
	v_lshl_or_b32 v128, v110, 16, v109
	v_lshl_or_b32 v129, v112, 16, v111
	global_store_dwordx2 v122, v[128:129], s[90:91]
	v_cvt_pk_fp8_f32 v109, v35, v39
	v_cvt_pk_fp8_f32 v110, v43, v47
	v_cvt_pk_fp8_f32 v111, v51, v55
	v_cvt_pk_fp8_f32 v112, v59, v63
	v_and_b32_e32 v109, 0xffff, v109
	v_and_b32_e32 v111, 0xffff, v111
	v_lshl_or_b32 v130, v110, 16, v109
	v_lshl_or_b32 v131, v112, 16, v111
	global_store_dwordx2 v123, v[130:131], s[90:91]
	s_waitcnt vmcnt(8)
; #define LAS __attribute__((address_space(3)))
; __device__ __forceinline__ void transpose_item_fp8(const float* W, int N, unsigned char* W8, int pitch, int kofs, int k0, int n_src, int n_dst, float scale, LAS float* scr, int lane) {
;     ...
;     for (int i = 0; i < 8; ++i) v[i] = *(const f32x4*)(W + (size_t)(k0 + r8 + 8 * i) * N + n_src + 4 * c4);
; #pragma unroll
;     for (int i = 0; i < 8; ++i) { LAS float* d = scr + (r8 + 8 * i) * 33 + 4 * c4; d[0] = v[i][0]; d[1] = v[i][1]; d[2] = v[i][2]; d[3] = v[i][3]; }
;     asm volatile("s_waitcnt lgkmcnt(0)" ::: "memory");
;     const int n = lane & 31, cp = lane >> 5;
; #pragma unroll
;     for (int q = 0; q < 2; ++q) { const int ck = (2 * cp + q) * 16; const LAS float* sp = scr + ck * 33 + n; u32x4 o;
; #pragma unroll
;         for (int w = 0; w < 4; ++w) o[w] = pack_fp8x4(sp[(4 * w) * 33] * scale, sp[(4 * w + 1) * 33] * scale, sp[(4 * w + 2) * 33] * scale, sp[(4 * w + 3) * 33] * scale);
;         *(u32x4*)(W8 + (size_t)(n_dst + n) * pitch + kofs + k0 + ck) = o; }
	v_pk_mul_f32 v[64:65], v[64:65], s[4:5]
	v_pk_mul_f32 v[66:67], v[66:67], s[4:5]
	v_pk_mul_f32 v[68:69], v[68:69], s[4:5]
	v_pk_mul_f32 v[70:71], v[70:71], s[4:5]
	v_pk_mul_f32 v[72:73], v[72:73], s[4:5]
	v_pk_mul_f32 v[74:75], v[74:75], s[4:5]
	v_pk_mul_f32 v[76:77], v[76:77], s[4:5]
	v_pk_mul_f32 v[78:79], v[78:79], s[4:5]
	v_pk_mul_f32 v[80:81], v[80:81], s[4:5]
	v_pk_mul_f32 v[82:83], v[82:83], s[4:5]
	v_pk_mul_f32 v[84:85], v[84:85], s[4:5]
	v_pk_mul_f32 v[86:87], v[86:87], s[4:5]
	v_pk_mul_f32 v[88:89], v[88:89], s[4:5]
	v_pk_mul_f32 v[90:91], v[90:91], s[4:5]
	v_pk_mul_f32 v[92:93], v[92:93], s[4:5]
	v_pk_mul_f32 v[94:95], v[94:95], s[4:5]
	v_cvt_pk_fp8_f32 v109, v64, v68
	v_cvt_pk_fp8_f32 v110, v72, v76
	v_cvt_pk_fp8_f32 v111, v80, v84
	v_cvt_pk_fp8_f32 v112, v88, v92
	v_and_b32_e32 v109, 0xffff, v109
	v_and_b32_e32 v111, 0xffff, v111
	v_lshl_or_b32 v128, v110, 16, v109
	v_lshl_or_b32 v129, v112, 16, v111
	global_store_dwordx2 v124, v[128:129], s[90:91]
	v_cvt_pk_fp8_f32 v109, v65, v69
	v_cvt_pk_fp8_f32 v110, v73, v77
	v_cvt_pk_fp8_f32 v111, v81, v85
	v_cvt_pk_fp8_f32 v112, v89, v93
	v_and_b32_e32 v109, 0xffff, v109
	v_and_b32_e32 v111, 0xffff, v111
	v_lshl_or_b32 v130, v110, 16, v109
	v_lshl_or_b32 v131, v112, 16, v111
	global_store_dwordx2 v125, v[130:131], s[90:91]
	v_cvt_pk_fp8_f32 v109, v66, v70
	v_cvt_pk_fp8_f32 v110, v74, v78
	v_cvt_pk_fp8_f32 v111, v82, v86
	v_cvt_pk_fp8_f32 v112, v90, v94
	v_and_b32_e32 v109, 0xffff, v109
	v_and_b32_e32 v111, 0xffff, v111
	v_lshl_or_b32 v128, v110, 16, v109
	v_lshl_or_b32 v129, v112, 16, v111
	global_store_dwordx2 v126, v[128:129], s[90:91]
	v_cvt_pk_fp8_f32 v109, v67, v71
	v_cvt_pk_fp8_f32 v110, v75, v79
	v_cvt_pk_fp8_f32 v111, v83, v87
	v_cvt_pk_fp8_f32 v112, v91, v95
	v_and_b32_e32 v109, 0xffff, v109
	v_and_b32_e32 v111, 0xffff, v111
	v_lshl_or_b32 v130, v110, 16, v109
	v_lshl_or_b32 v131, v112, 16, v111
	global_store_dwordx2 v127, v[130:131], s[90:91]
	s_branch .LBB0_279
; #define LAS __attribute__((address_space(3)))
; __device__ __forceinline__ void transpose_item_fp8(const float* W, int N, unsigned char* W8, int pitch, int kofs, int k0, int n_src, int n_dst, float scale, LAS float* scr, int lane) {
;     const int r8 = lane >> 3, c4 = lane & 7;
;     f32x4 v[8];
; #pragma unroll
;     for (int i = 0; i < 8; ++i) v[i] = *(const f32x4*)(W + (size_t)(k0 + r8 + 8 * i) * N + n_src + 4 * c4);
; #pragma unroll
;     for (int i = 0; i < 8; ++i) { LAS float* d = scr + (r8 + 8 * i) * 33 + 4 * c4; d[0] = v[i][0]; d[1] = v[i][1]; d[2] = v[i][2]; d[3] = v[i][3]; }
;     asm volatile("s_waitcnt lgkmcnt(0)" ::: "memory");
;     const int n = lane & 31, cp = lane >> 5;
; #pragma unroll
;     for (int q = 0; q < 2; ++q) { const int ck = (2 * cp + q) * 16; const LAS float* sp = scr + ck * 33 + n; u32x4 o;
; #pragma unroll
;         for (int w = 0; w < 4; ++w) o[w] = pack_fp8x4(sp[(4 * w) * 33] * scale, sp[(4 * w + 1) * 33] * scale, sp[(4 * w + 2) * 33] * scale, sp[(4 * w + 3) * 33] * scale);
;         *(u32x4*)(W8 + (size_t)(n_dst + n) * pitch + kofs + k0 + ck) = o; }
;     asm volatile("s_waitcnt lgkmcnt(0)" ::: "memory");
; }
; __global__ void __launch_bounds__(512, 2) hybrid_fwd(Args a) {
;     ...
;                 for (int it = gw; it < I_PA + I_PB + I_OUT; it += NGW) {
;                     int r = it;
;                     if (r < I_PA) { const int nb = r % (D / 32), kb = r / (D / 32); transpose_item_fp8(a.w_pa, D, Wp8, 1536, 0, 64 * kb, 32 * nb, 32 * nb, W8_SCALE, scr, lane); continue; } r -= I_PA;
;                     if (r < I_PB) { const int nb = r % (D / 32), kb = r / (D / 32); transpose_item_fp8(a.w_pb, D, Wp8, 1536, 1024, 64 * kb, 32 * nb, 32 * nb, W8_SCALE, scr, lane); continue; } r -= I_PB;
;                     { const int nb = r % (D / 32), kb = r / (D / 32); transpose_item_fp8(a.w_out, D, Wout8, 2048, 0, 64 * kb, 32 * nb, 32 * nb, W8_SCALE, scr, lane); }
.Ltail_two:
	s_mov_b32 s4, 0x42800000
	s_mov_b32 s5, 0x42800000
	s_waitcnt vmcnt(8)
	v_pk_mul_f32 v[0:1], v[0:1], s[4:5]
	v_pk_mul_f32 v[2:3], v[2:3], s[4:5]
	v_pk_mul_f32 v[4:5], v[4:5], s[4:5]
	v_pk_mul_f32 v[6:7], v[6:7], s[4:5]
	v_pk_mul_f32 v[8:9], v[8:9], s[4:5]
	v_pk_mul_f32 v[10:11], v[10:11], s[4:5]
	v_pk_mul_f32 v[12:13], v[12:13], s[4:5]
	v_pk_mul_f32 v[14:15], v[14:15], s[4:5]
	v_pk_mul_f32 v[16:17], v[16:17], s[4:5]
	v_pk_mul_f32 v[18:19], v[18:19], s[4:5]
	v_pk_mul_f32 v[20:21], v[20:21], s[4:5]
	v_pk_mul_f32 v[22:23], v[22:23], s[4:5]
	v_pk_mul_f32 v[24:25], v[24:25], s[4:5]
	v_pk_mul_f32 v[26:27], v[26:27], s[4:5]
	v_pk_mul_f32 v[28:29], v[28:29], s[4:5]
	v_pk_mul_f32 v[30:31], v[30:31], s[4:5]
	v_cvt_pk_fp8_f32 v109, v0, v4
	v_cvt_pk_fp8_f32 v110, v8, v12
	v_cvt_pk_fp8_f32 v111, v16, v20
	v_cvt_pk_fp8_f32 v112, v24, v28
	v_and_b32_e32 v109, 0xffff, v109
	v_and_b32_e32 v111, 0xffff, v111
	v_lshl_or_b32 v128, v110, 16, v109
	v_lshl_or_b32 v129, v112, 16, v111
	global_store_dwordx2 v116, v[128:129], s[90:91]
	v_cvt_pk_fp8_f32 v109, v1, v5
	v_cvt_pk_fp8_f32 v110, v9, v13
	v_cvt_pk_fp8_f32 v111, v17, v21
	v_cvt_pk_fp8_f32 v112, v25, v29
	v_and_b32_e32 v109, 0xffff, v109
	v_and_b32_e32 v111, 0xffff, v111
	v_lshl_or_b32 v130, v110, 16, v109
	v_lshl_or_b32 v131, v112, 16, v111
	global_store_dwordx2 v117, v[130:131], s[90:91]
	v_cvt_pk_fp8_f32 v109, v2, v6
	v_cvt_pk_fp8_f32 v110, v10, v14
	v_cvt_pk_fp8_f32 v111, v18, v22
	v_cvt_pk_fp8_f32 v112, v26, v30
	v_and_b32_e32 v109, 0xffff, v109
	v_and_b32_e32 v111, 0xffff, v111
	v_lshl_or_b32 v128, v110, 16, v109
	v_lshl_or_b32 v129, v112, 16, v111
	global_store_dwordx2 v118, v[128:129], s[90:91]
	v_cvt_pk_fp8_f32 v109, v3, v7
	v_cvt_pk_fp8_f32 v110, v11, v15
	v_cvt_pk_fp8_f32 v111, v19, v23
	v_cvt_pk_fp8_f32 v112, v27, v31
	v_and_b32_e32 v109, 0xffff, v109
	v_and_b32_e32 v111, 0xffff, v111
	v_lshl_or_b32 v130, v110, 16, v109
	v_lshl_or_b32 v131, v112, 16, v111
	global_store_dwordx2 v119, v[130:131], s[90:91]
	s_waitcnt vmcnt(4)
	v_pk_mul_f32 v[32:33], v[32:33], s[4:5]
	v_pk_mul_f32 v[34:35], v[34:35], s[4:5]
	v_pk_mul_f32 v[36:37], v[36:37], s[4:5]
	v_pk_mul_f32 v[38:39], v[38:39], s[4:5]
	v_pk_mul_f32 v[40:41], v[40:41], s[4:5]
	v_pk_mul_f32 v[42:43], v[42:43], s[4:5]
	v_pk_mul_f32 v[44:45], v[44:45], s[4:5]
	v_pk_mul_f32 v[46:47], v[46:47], s[4:5]
	v_pk_mul_f32 v[48:49], v[48:49], s[4:5]
	v_pk_mul_f32 v[50:51], v[50:51], s[4:5]
	v_pk_mul_f32 v[52:53], v[52:53], s[4:5]
	v_pk_mul_f32 v[54:55], v[54:55], s[4:5]
	v_pk_mul_f32 v[56:57], v[56:57], s[4:5]
	v_pk_mul_f32 v[58:59], v[58:59], s[4:5]
	v_pk_mul_f32 v[60:61], v[60:61], s[4:5]
	v_pk_mul_f32 v[62:63], v[62:63], s[4:5]
	v_cvt_pk_fp8_f32 v109, v32, v36
	v_cvt_pk_fp8_f32 v110, v40, v44
	v_cvt_pk_fp8_f32 v111, v48, v52
	v_cvt_pk_fp8_f32 v112, v56, v60
	v_and_b32_e32 v109, 0xffff, v109
	v_and_b32_e32 v111, 0xffff, v111
	v_lshl_or_b32 v128, v110, 16, v109
	v_lshl_or_b32 v129, v112, 16, v111
	global_store_dwordx2 v120, v[128:129], s[90:91]
	v_cvt_pk_fp8_f32 v109, v33, v37
	v_cvt_pk_fp8_f32 v110, v41, v45
	v_cvt_pk_fp8_f32 v111, v49, v53
	v_cvt_pk_fp8_f32 v112, v57, v61
	v_and_b32_e32 v109, 0xffff, v109
	v_and_b32_e32 v111, 0xffff, v111
	v_lshl_or_b32 v130, v110, 16, v109
	v_lshl_or_b32 v131, v112, 16, v111
	global_store_dwordx2 v121, v[130:131], s[90:91]
	v_cvt_pk_fp8_f32 v109, v34, v38
	v_cvt_pk_fp8_f32 v110, v42, v46
	v_cvt_pk_fp8_f32 v111, v50, v54
	v_cvt_pk_fp8_f32 v112, v58, v62
	v_and_b32_e32 v109, 0xffff, v109
	v_and_b32_e32 v111, 0xffff, v111
	v_lshl_or_b32 v128, v110, 16, v109
	v_lshl_or_b32 v129, v112, 16, v111
	global_store_dwordx2 v122, v[128:129], s[90:91]
	v_cvt_pk_fp8_f32 v109, v35, v39
	v_cvt_pk_fp8_f32 v110, v43, v47
	v_cvt_pk_fp8_f32 v111, v51, v55
	v_cvt_pk_fp8_f32 v112, v59, v63
	v_and_b32_e32 v109, 0xffff, v109
	v_and_b32_e32 v111, 0xffff, v111
	v_lshl_or_b32 v130, v110, 16, v109
	v_lshl_or_b32 v131, v112, 16, v111
	global_store_dwordx2 v123, v[130:131], s[90:91]
	s_branch .LBB0_279
.Ltail_orig:
	s_sub_i32 s1, s2, s0
	s_lshl_b32 s1, s1, 3
	v_readlane_b32 s4, v242, 0
	s_add_i32 s8, s1, s4
	s_cmpk_gt_u32 s8, 0xdff
	s_cbranch_scc1 .LBB0_279
	s_sub_i32 s4, s92, s0
	s_load_dwordx4 s[12:15], s[70:71], 0x28
	s_load_dwordx2 s[0:1], s[70:71], 0x38
	v_and_b32_e32 v0, 7, v160
	v_lshrrev_b32_e32 v8, 3, v192
	v_lshlrev_b32_e32 v0, 4, v0
	v_mov_b32_e32 v1, 0
	v_and_b32_e32 v9, 31, v160
	s_waitcnt lgkmcnt(0)
	v_lshl_add_u64 v[2:3], s[0:1], 0, v[0:1]
	v_add_u32_e32 v11, s31, v0
	v_mul_u32_u24_e32 v12, 0x84, v8
	v_lshl_add_u32 v26, v9, 2, s31
	v_mul_u32_u24_e32 v27, 0x84, v162
	s_mul_i32 s0, s8, 0xc000
	v_lshl_add_u64 v[4:5], s[14:15], 0, v[0:1]
	v_lshl_add_u64 v[6:7], s[12:13], 0, v[0:1]
	s_movk_i32 s1, 0x600
	v_mov_b32_e32 v0, s0
	v_add_u32_e32 v11, v11, v12
	v_add_u32_e32 v26, v26, v27
	s_lshl_b32 s9, s4, 3
	v_mov_b32_e32 v163, v1
	v_mad_u32_u24 v10, v9, s1, v0
	s_mul_i32 s10, s4, 0x60000
	s_lshl_b32 s11, s8, 5
	s_lshl_b32 s12, s4, 8
	s_mov_b32 s1, 0
	v_add_u32_e32 v12, 0x420, v11
	v_add_u32_e32 v13, 0x428, v11
	v_add_u32_e32 v14, 0x840, v11
	v_add_u32_e32 v15, 0x848, v11
	v_add_u32_e32 v16, 0xc60, v11
	v_add_u32_e32 v17, 0xc68, v11
	v_add_u32_e32 v18, 0x1080, v11
	v_add_u32_e32 v19, 0x1088, v11
	v_add_u32_e32 v20, 0x14a0, v11
	v_add_u32_e32 v21, 0x14a8, v11
	v_add_u32_e32 v22, 0x18c0, v11
	v_add_u32_e32 v23, 0x18c8, v11
	v_add_u32_e32 v24, 0x1ce0, v11
	v_add_u32_e32 v25, 0x1ce8, v11
	v_add_u32_e32 v27, 0x400, v26
	v_add_u32_e32 v28, 0x800, v26
	v_add_u32_e32 v29, 0xc00, v26
	s_branch .LBB0_271
